# v33: v20 + P0 weight-transpose items (FFN gate/up and down): the 8 row loads of an item issued together with counted waits instead of one load per full wait
# baseline (speedup 1.0000x reference)
; #define LAS __attribute__((address_space(3)))
; __device__ __forceinline__ void transpose_item(const float* W, int K, int N, bf16_t* WT, int mode, int sel, LAS float* scr, int item, int lane) {
;     const int nblk = N / 32, kb = item / nblk, nb = item - kb * nblk, k0 = 64 * kb, n0 = 32 * nb;
;     const int l7 = lane & 7, l3 = lane >> 3;
; #pragma unroll
;     for (int i = 0; i < 8; ++i) {
;         const int kk = l3 + 8 * i;
;         const f32x4 v = *(const f32x4*)(W + (size_t)(k0 + kk) * N + n0 + l7 * 4);
;         LAS float* s = scr + kk * 33 + l7 * 4;
;         s[0] = v[0]; s[1] = v[1]; s[2] = v[2]; s[3] = v[3];
;     }
; __global__ void __launch_bounds__(512, 2) mk_fwd(Params p) {
;     ...
;                     const int mi = r / I_FFN; r -= mi * I_FFN;
;                     const int fab = mi / 6, rem = mi - fab * 6, fl = rem / 3, kind = rem - fl * 3;
;                     const float* src = (const float*)karg_ptr_dyn(8 * (4 + fab * 5 + kind));
;                     src += (size_t)fl * D * FF;
;                     if (kind < 2) transpose_item(src, D, FF, (bf16_t*)(ws + WS_WGU + (size_t)(fab * 2 + fl) * 44 * MiB), MAP_GU, kind, scr, r, lane);
;                     else transpose_item(src, FF, D, (bf16_t*)(ws + WS_WD + (size_t)(fab * 2 + fl) * 22 * MiB), MAP_PLAIN, 0, scr, r, lane);
.LBB0_351:
	s_andn2_b64 vcc, exec, s[4:5]
	s_cbranch_vccnz .LBB0_320
	s_mul_hi_i32 s4, s42, 0x2e8ba2e9
	s_lshr_b32 s5, s4, 31
	s_ashr_i32 s43, s4, 10
	s_add_i32 s43, s43, s5
	s_mul_i32 s4, s43, 0xffffea00
	s_add_i32 s44, s42, s4
	s_mul_hi_i32 s4, s42, 0x3e0f83e1
	s_lshr_b32 s5, s4, 31
	s_ashr_i32 s4, s4, 13
	s_add_i32 s47, s4, s5
	s_mul_i32 s4, s47, -6
	s_add_i32 s4, s4, s43
	s_mul_hi_i32 s5, s4, 0x55555556
	s_lshr_b32 s26, s5, 31
	s_add_i32 s48, s5, s26
	s_mul_i32 s26, s48, -3
	s_add_i32 s26, s26, s4
	s_mul_i32 s4, s47, 5
	s_add_i32 s4, s4, s26
	s_add_i32 s4, s4, 4
	s_lshl_b32 s4, s4, 3
	s_mul_i32 s45, s48, 0x2c00000
	s_load_dwordx2 s[4:5], s[0:1], s4
	s_waitcnt lgkmcnt(0)
	s_mul_hi_i32 s46, s48, 0x2c00000
	s_add_u32 s45, s4, s45
	s_addc_u32 s46, s5, s46
	s_lshl_b32 s4, s47, 1
	s_add_i32 s47, s48, s4
	v_add_u32_e32 v47, v7, v24
	s_cmp_gt_i32 s26, 1
	s_mov_b64 s[4:5], -1
	v_lshlrev_b32_e32 v176, 2, v4
	v_add_u32_e32 v45, 0x420, v47
	v_add_u32_e32 v46, 0x428, v47
	v_add_u32_e32 v43, 0x840, v47
	v_add_u32_e32 v44, 0x848, v47
	v_add_u32_e32 v41, 0xc60, v47
	v_add_u32_e32 v42, 0xc68, v47
	v_add_u32_e32 v39, 0x1080, v47
	v_add_u32_e32 v40, 0x1088, v47
	v_add_u32_e32 v22, 0x14a0, v47
	v_add_u32_e32 v23, 0x14a8, v47
	v_add_u32_e32 v20, 0x18c0, v47
	v_add_u32_e32 v21, 0x18c8, v47
	v_add_u32_e32 v2, 0x1ce0, v47
	v_add_u32_e32 v3, 0x1ce8, v47
	v_lshlrev_b32_e32 v0, 1, v6
	s_cbranch_scc0 .LBB0_354
	s_mul_i32 s4, s47, 22
	s_ashr_i32 s5, s4, 31
	s_lshl_b64 s[4:5], s[4:5], 20
	s_add_u32 s50, s3, s4
	s_addc_u32 s51, s6, s5
	s_ashr_i32 s4, s44, 31
	s_lshr_b32 s4, s4, 26
	s_add_i32 s5, s44, s4
	s_and_b32 s4, s5, 0xffffffc0
	s_lshl_b32 s5, s5, 5
	s_and_b32 s5, s5, 0xfffff800
	s_mul_i32 s48, s43, 0x2c000
	s_add_i32 s52, s5, s48
	s_add_i32 s5, s11, s41
	s_sub_i32 s48, s5, s52
	s_ashr_i32 s49, s48, 31
	s_lshl_b64 s[48:49], s[48:49], 2
	s_add_u32 s48, s45, s48
	v_or_b32_e32 v48, s4, v5
	s_addc_u32 s49, s46, s49
	v_ashrrev_i32_e32 v49, 31, v48
	v_lshl_add_u64 v[52:53], s[48:49], 0, v[176:177]
	v_lshlrev_b64 v[48:49], 13, v[48:49]
	v_lshl_add_u64 v[48:49], v[52:53], 0, v[48:49]
	v_or_b32_e32 v148, s4, v5
	v_ashrrev_i32_e32 v149, 31, v148
	v_lshlrev_b64 v[148:149], 13, v[148:149]
	v_lshl_add_u64 v[132:133], v[52:53], 0, v[148:149]
	global_load_dwordx4 v[100:103], v[132:133], off
	v_or_b32_e32 v148, s4, v25
	v_ashrrev_i32_e32 v149, 31, v148
	v_lshlrev_b64 v[148:149], 13, v[148:149]
	v_lshl_add_u64 v[134:135], v[52:53], 0, v[148:149]
	global_load_dwordx4 v[104:107], v[134:135], off
	v_or_b32_e32 v148, s4, v26
	v_ashrrev_i32_e32 v149, 31, v148
	v_lshlrev_b64 v[148:149], 13, v[148:149]
	v_lshl_add_u64 v[136:137], v[52:53], 0, v[148:149]
	global_load_dwordx4 v[108:111], v[136:137], off
	v_or_b32_e32 v148, s4, v27
	v_ashrrev_i32_e32 v149, 31, v148
	v_lshlrev_b64 v[148:149], 13, v[148:149]
	v_lshl_add_u64 v[138:139], v[52:53], 0, v[148:149]
	global_load_dwordx4 v[112:115], v[138:139], off
	v_or_b32_e32 v148, s4, v28
	v_ashrrev_i32_e32 v149, 31, v148
	v_lshlrev_b64 v[148:149], 13, v[148:149]
	v_lshl_add_u64 v[140:141], v[52:53], 0, v[148:149]
	global_load_dwordx4 v[116:119], v[140:141], off
	v_or_b32_e32 v148, s4, v29
	v_ashrrev_i32_e32 v149, 31, v148
	v_lshlrev_b64 v[148:149], 13, v[148:149]
	v_lshl_add_u64 v[142:143], v[52:53], 0, v[148:149]
	global_load_dwordx4 v[120:123], v[142:143], off
	v_or_b32_e32 v148, s4, v30
	v_ashrrev_i32_e32 v149, 31, v148
	v_lshlrev_b64 v[148:149], 13, v[148:149]
	v_lshl_add_u64 v[144:145], v[52:53], 0, v[148:149]
	global_load_dwordx4 v[124:127], v[144:145], off
	v_or_b32_e32 v148, s4, v31
	v_ashrrev_i32_e32 v149, 31, v148
	v_lshlrev_b64 v[148:149], 13, v[148:149]
	v_lshl_add_u64 v[146:147], v[52:53], 0, v[148:149]
	global_load_dwordx4 v[128:131], v[146:147], off
	v_or_b32_e32 v54, s4, v25
	v_ashrrev_i32_e32 v55, 31, v54
	v_lshlrev_b64 v[54:55], 13, v[54:55]
	v_lshl_add_u64 v[54:55], v[52:53], 0, v[54:55]
	s_ashr_i32 s5, s4, 31
	v_mov_b32_e32 v1, v177
	s_waitcnt vmcnt(7)
	ds_write2_b32 v47, v100, v101 offset1:1
	ds_write2_b32 v47, v102, v103 offset0:2 offset1:3
	v_or_b32_e32 v54, s4, v26
	v_ashrrev_i32_e32 v55, 31, v54
	v_lshlrev_b64 v[54:55], 13, v[54:55]
	v_lshl_add_u64 v[54:55], v[52:53], 0, v[54:55]
	s_waitcnt vmcnt(6)
	ds_write2_b32 v45, v104, v105 offset1:1
	ds_write2_b32 v46, v106, v107 offset1:1
	v_or_b32_e32 v54, s4, v27
	v_ashrrev_i32_e32 v55, 31, v54
	v_lshlrev_b64 v[54:55], 13, v[54:55]
	v_lshl_add_u64 v[54:55], v[52:53], 0, v[54:55]
	s_waitcnt vmcnt(5)
	ds_write2_b32 v43, v108, v109 offset1:1
	ds_write2_b32 v44, v110, v111 offset1:1
	v_or_b32_e32 v54, s4, v28
	v_ashrrev_i32_e32 v55, 31, v54
	v_lshlrev_b64 v[54:55], 13, v[54:55]
	v_lshl_add_u64 v[54:55], v[52:53], 0, v[54:55]
	s_waitcnt vmcnt(4)
	ds_write2_b32 v41, v112, v113 offset1:1
	ds_write2_b32 v42, v114, v115 offset1:1
	v_or_b32_e32 v54, s4, v29
	v_ashrrev_i32_e32 v55, 31, v54
	v_lshlrev_b64 v[54:55], 13, v[54:55]
	v_lshl_add_u64 v[54:55], v[52:53], 0, v[54:55]
	s_waitcnt vmcnt(3)
	ds_write2_b32 v39, v116, v117 offset1:1
	ds_write2_b32 v40, v118, v119 offset1:1
	v_or_b32_e32 v54, s4, v30
	v_ashrrev_i32_e32 v55, 31, v54
	v_lshlrev_b64 v[54:55], 13, v[54:55]
	v_lshl_add_u64 v[54:55], v[52:53], 0, v[54:55]
	s_waitcnt vmcnt(2)
	ds_write2_b32 v22, v120, v121 offset1:1
	ds_write2_b32 v23, v122, v123 offset1:1
	v_or_b32_e32 v54, s4, v31
	v_ashrrev_i32_e32 v55, 31, v54
	v_lshlrev_b64 v[54:55], 13, v[54:55]
	v_lshl_add_u64 v[52:53], v[52:53], 0, v[54:55]
	s_lshl_b64 s[4:5], s[4:5], 1
	s_add_u32 s4, s50, s4
	s_addc_u32 s5, s51, s5
	s_sub_i32 s48, s41, s52
	s_waitcnt vmcnt(1)
; #define LAS __attribute__((address_space(3)))
; __device__ __forceinline__ unsigned cvt_pk_bf16(float lo, float hi) { unsigned r; asm("v_cvt_pk_bf16_f32 %0, %1, %2" : "=v"(r) : "v"(lo), "v"(hi)); return r; }
; #define LDS_WAIT() asm volatile("s_waitcnt lgkmcnt(0)" ::: "memory")
; __device__ __forceinline__ void transpose_item(const float* W, int K, int N, bf16_t* WT, int mode, int sel, LAS float* scr, int item, int lane) {
;     ...
;         s[0] = v[0]; s[1] = v[1]; s[2] = v[2]; s[3] = v[3];
;     }
;     LDS_WAIT(); asm volatile("" ::: "memory");
; #pragma unroll
;     for (int j = 0; j < 4; ++j) {
;         const int n = l3 + 8 * j; const LAS float* s = scr + (8 * l7) * 33 + n;
;         u32x4 o; o.x = cvt_pk_bf16(s[0 * 33], s[1 * 33]); o.y = cvt_pk_bf16(s[2 * 33], s[3 * 33]); o.z = cvt_pk_bf16(s[4 * 33], s[5 * 33]); o.w = cvt_pk_bf16(s[6 * 33], s[7 * 33]);
;         *(u32x4*)(WT + (size_t)map_row(mode, n0 + n, sel) * K + k0 + 8 * l7) = o;
;     }
;     LDS_WAIT(); asm volatile("" ::: "memory");
	ds_write2_b32 v20, v124, v125 offset1:1
	ds_write2_b32 v21, v126, v127 offset1:1
	v_lshl_add_u64 v[52:53], s[4:5], 0, v[0:1]
	v_add_u32_e32 v1, s48, v38
	v_mad_i64_i32 v[54:55], s[4:5], v1, s80, v[52:53]
	v_add_u32_e32 v56, 8, v1
	v_add_u32_e32 v61, 16, v1
	v_add_u32_e32 v1, 24, v1
	s_waitcnt vmcnt(0)
	ds_write2_b32 v2, v128, v129 offset1:1
	ds_write2_b32 v3, v130, v131 offset1:1
	s_waitcnt lgkmcnt(0)
	ds_read_b32 v48, v32
	ds_read_b32 v49, v32 offset:132
	ds_read_b32 v50, v32 offset:264
	ds_read_b32 v51, v32 offset:396
	ds_read_b32 v57, v32 offset:528
	ds_read_b32 v58, v32 offset:660
	ds_read_b32 v59, v32 offset:792
	ds_read_b32 v60, v32 offset:924
	s_waitcnt lgkmcnt(6)
	v_cvt_pk_bf16_f32 v48, v48, v49
	s_waitcnt lgkmcnt(4)
	v_cvt_pk_bf16_f32 v49, v50, v51
	s_waitcnt lgkmcnt(2)
	v_cvt_pk_bf16_f32 v50, v57, v58
	s_waitcnt lgkmcnt(0)
	v_cvt_pk_bf16_f32 v51, v59, v60
	flat_store_dwordx4 v[54:55], v[48:51]
	ds_read_b32 v48, v32 offset:32
	ds_read_b32 v49, v32 offset:164
	ds_read_b32 v50, v32 offset:296
	ds_read_b32 v51, v32 offset:428
	ds_read_b32 v57, v32 offset:560
	ds_read_b32 v58, v32 offset:692
	ds_read_b32 v59, v32 offset:824
	ds_read_b32 v60, v32 offset:956
	v_mad_i64_i32 v[54:55], s[4:5], v56, s80, v[52:53]
	s_waitcnt lgkmcnt(0)
	v_cvt_pk_bf16_f32 v48, v48, v49
	v_cvt_pk_bf16_f32 v49, v50, v51
	v_cvt_pk_bf16_f32 v50, v57, v58
	v_cvt_pk_bf16_f32 v51, v59, v60
	flat_store_dwordx4 v[54:55], v[48:51]
	ds_read_b32 v48, v32 offset:64
	ds_read_b32 v49, v32 offset:196
	ds_read_b32 v50, v32 offset:328
	ds_read_b32 v51, v32 offset:460
	ds_read_b32 v56, v32 offset:592
	ds_read_b32 v57, v32 offset:724
	ds_read_b32 v58, v32 offset:856
	ds_read_b32 v59, v32 offset:988
	v_mad_i64_i32 v[54:55], s[4:5], v61, s80, v[52:53]
	s_waitcnt lgkmcnt(0)
	v_cvt_pk_bf16_f32 v48, v48, v49
	v_cvt_pk_bf16_f32 v49, v50, v51
	v_cvt_pk_bf16_f32 v50, v56, v57
	v_cvt_pk_bf16_f32 v51, v58, v59
	flat_store_dwordx4 v[54:55], v[48:51]
	ds_read_b32 v48, v32 offset:96
	ds_read_b32 v49, v32 offset:228
	ds_read_b32 v50, v32 offset:360
	ds_read_b32 v51, v32 offset:492
	ds_read_b32 v54, v32 offset:624
	ds_read_b32 v55, v32 offset:756
	ds_read_b32 v56, v32 offset:888
	ds_read_b32 v57, v32 offset:1020
	v_mad_i64_i32 v[52:53], s[4:5], v1, s80, v[52:53]
	s_waitcnt lgkmcnt(0)
	v_cvt_pk_bf16_f32 v48, v48, v49
	v_cvt_pk_bf16_f32 v49, v50, v51
	v_cvt_pk_bf16_f32 v50, v54, v55
	v_cvt_pk_bf16_f32 v51, v56, v57
	flat_store_dwordx4 v[52:53], v[48:51]
	s_waitcnt lgkmcnt(0)
	s_mov_b64 s[4:5], 0
; #define LAS __attribute__((address_space(3)))
; __device__ __forceinline__ unsigned cvt_pk_bf16(float lo, float hi) { unsigned r; asm("v_cvt_pk_bf16_f32 %0, %1, %2" : "=v"(r) : "v"(lo), "v"(hi)); return r; }
; #define LDS_WAIT() asm volatile("s_waitcnt lgkmcnt(0)" ::: "memory")
; __device__ __forceinline__ void transpose_item(const float* W, int K, int N, bf16_t* WT, int mode, int sel, LAS float* scr, int item, int lane) {
;     const int nblk = N / 32, kb = item / nblk, nb = item - kb * nblk, k0 = 64 * kb, n0 = 32 * nb;
;     const int l7 = lane & 7, l3 = lane >> 3;
; #pragma unroll
;     for (int i = 0; i < 8; ++i) {
;         const int kk = l3 + 8 * i;
;         const f32x4 v = *(const f32x4*)(W + (size_t)(k0 + kk) * N + n0 + l7 * 4);
;         LAS float* s = scr + kk * 33 + l7 * 4;
;         s[0] = v[0]; s[1] = v[1]; s[2] = v[2]; s[3] = v[3];
;     }
;     LDS_WAIT(); asm volatile("" ::: "memory");
; #pragma unroll
;     for (int j = 0; j < 4; ++j) {
;         const int n = l3 + 8 * j; const LAS float* s = scr + (8 * l7) * 33 + n;
;         u32x4 o; o.x = cvt_pk_bf16(s[0 * 33], s[1 * 33]); o.y = cvt_pk_bf16(s[2 * 33], s[3 * 33]); o.z = cvt_pk_bf16(s[4 * 33], s[5 * 33]); o.w = cvt_pk_bf16(s[6 * 33], s[7 * 33]);
;         *(u32x4*)(WT + (size_t)map_row(mode, n0 + n, sel) * K + k0 + 8 * l7) = o;
;     }
;     LDS_WAIT(); asm volatile("" ::: "memory");
.LBB0_354:
	s_andn2_b64 vcc, exec, s[4:5]
	s_cbranch_vccnz .LBB0_320
	s_mul_i32 s4, s47, 44
	s_ashr_i32 s5, s4, 31
	s_lshl_b64 s[4:5], s[4:5], 20
	s_add_u32 s50, s7, s4
	s_mul_hi_i32 s4, s44, 0x2e8ba2e9
	s_addc_u32 s51, s10, s5
	s_lshr_b32 s5, s4, 31
	s_ashr_i32 s4, s4, 5
	s_add_i32 s4, s4, s5
	s_mul_i32 s5, s4, 0xffffff50
	s_mulk_i32 s43, 0x1600
	s_sub_i32 s5, s5, s43
	s_add_i32 s43, s42, s5
	s_lshl_b32 s44, s4, 6
	s_lshl_b32 s4, s43, 5
	s_ashr_i32 s5, s4, 31
	s_lshl_b64 s[48:49], s[4:5], 2
	s_add_u32 s48, s45, s48
	s_addc_u32 s49, s46, s49
	v_lshl_add_u64 v[52:53], s[48:49], 0, v[176:177]
	v_or_b32_e32 v1, s44, v5
	v_mad_i64_i32 v[48:49], s[46:47], v1, s81, v[52:53]
	v_or_b32_e32 v148, s44, v5
	v_mad_i64_i32 v[132:133], s[46:47], v148, s81, v[52:53]
	global_load_dwordx4 v[100:103], v[132:133], off
	v_or_b32_e32 v148, s44, v25
	v_mad_i64_i32 v[134:135], s[46:47], v148, s81, v[52:53]
	global_load_dwordx4 v[104:107], v[134:135], off
	v_or_b32_e32 v148, s44, v26
	v_mad_i64_i32 v[136:137], s[46:47], v148, s81, v[52:53]
	global_load_dwordx4 v[108:111], v[136:137], off
	v_or_b32_e32 v148, s44, v27
	v_mad_i64_i32 v[138:139], s[46:47], v148, s81, v[52:53]
	global_load_dwordx4 v[112:115], v[138:139], off
	v_or_b32_e32 v148, s44, v28
	v_mad_i64_i32 v[140:141], s[46:47], v148, s81, v[52:53]
	global_load_dwordx4 v[116:119], v[140:141], off
	v_or_b32_e32 v148, s44, v29
	v_mad_i64_i32 v[142:143], s[46:47], v148, s81, v[52:53]
	global_load_dwordx4 v[120:123], v[142:143], off
	v_or_b32_e32 v148, s44, v30
	v_mad_i64_i32 v[144:145], s[46:47], v148, s81, v[52:53]
	global_load_dwordx4 v[124:127], v[144:145], off
	v_or_b32_e32 v148, s44, v31
	v_mad_i64_i32 v[146:147], s[46:47], v148, s81, v[52:53]
	global_load_dwordx4 v[128:131], v[146:147], off
	v_or_b32_e32 v1, s44, v25
	v_mad_i64_i32 v[54:55], s[46:47], v1, s81, v[52:53]
	v_or_b32_e32 v1, s44, v26
	s_lshl_b32 s5, s43, 6
	s_lshl_b32 s26, s26, 7
	s_ashr_i32 s45, s44, 31
	s_and_b32 s5, s5, 0xffffff00
	s_add_i32 s5, s5, s26
	s_waitcnt vmcnt(7)
	ds_write2_b32 v47, v100, v101 offset1:1
	ds_write2_b32 v47, v102, v103 offset0:2 offset1:3
	v_mad_i64_i32 v[54:55], s[46:47], v1, s81, v[52:53]
	v_or_b32_e32 v1, s44, v27
	s_waitcnt vmcnt(6)
	ds_write2_b32 v45, v104, v105 offset1:1
	ds_write2_b32 v46, v106, v107 offset1:1
	v_mad_i64_i32 v[50:51], s[46:47], v1, s81, v[52:53]
	v_or_b32_e32 v1, s44, v28
	s_waitcnt vmcnt(5)
	ds_write2_b32 v43, v108, v109 offset1:1
	ds_write2_b32 v44, v110, v111 offset1:1
	v_mad_i64_i32 v[48:49], s[46:47], v1, s81, v[52:53]
	v_or_b32_e32 v1, s44, v29
	s_waitcnt vmcnt(4)
	ds_write2_b32 v41, v112, v113 offset1:1
	ds_write2_b32 v42, v114, v115 offset1:1
	v_mad_i64_i32 v[46:47], s[46:47], v1, s81, v[52:53]
	v_or_b32_e32 v1, s44, v30
	s_waitcnt vmcnt(3)
	ds_write2_b32 v39, v116, v117 offset1:1
	ds_write2_b32 v40, v118, v119 offset1:1
	v_mad_i64_i32 v[44:45], s[46:47], v1, s81, v[52:53]
	v_or_b32_e32 v1, s44, v31
	s_lshl_b64 s[44:45], s[44:45], 1
	s_add_u32 s44, s50, s44
	s_addc_u32 s45, s51, s45
	s_and_b32 s4, s4, 0x60
	v_or_b32_e32 v39, s4, v26
	s_waitcnt vmcnt(2)
	ds_write2_b32 v22, v120, v121 offset1:1
	ds_write2_b32 v23, v122, v123 offset1:1
	v_mad_i64_i32 v[22:23], s[46:47], v1, s81, v[52:53]
	v_mov_b32_e32 v1, v177
	v_or_b32_e32 v44, s5, v39
	v_ashrrev_i32_e32 v45, 31, v44
	v_lshlrev_b64 v[44:45], 12, v[44:45]
	s_waitcnt vmcnt(1)
	ds_write2_b32 v20, v124, v125 offset1:1
	ds_write2_b32 v21, v126, v127 offset1:1
	v_lshl_add_u64 v[40:41], s[44:45], 0, v[0:1]
	v_or_b32_e32 v0, s4, v5
	v_or_b32_e32 v1, s4, v25
	v_or_b32_e32 v0, s5, v0
	v_or_b32_e32 v42, s5, v1
	v_ashrrev_i32_e32 v1, 31, v0
	v_lshlrev_b64 v[0:1], 12, v[0:1]
	v_or_b32_e32 v43, s4, v27
	v_or_b32_e32 v46, s5, v43
	v_ashrrev_i32_e32 v43, 31, v42
	v_lshlrev_b64 v[42:43], 12, v[42:43]
	v_ashrrev_i32_e32 v47, 31, v46
	s_waitcnt vmcnt(0)
	ds_write2_b32 v2, v128, v129 offset1:1
	ds_write2_b32 v3, v130, v131 offset1:1
	s_waitcnt lgkmcnt(0)
	ds_read_b32 v2, v32
	ds_read_b32 v3, v32 offset:132
	ds_read_b32 v22, v32 offset:264
	ds_read_b32 v23, v32 offset:396
	ds_read_b32 v39, v32 offset:528
	ds_read_b32 v48, v32 offset:660
	ds_read_b32 v49, v32 offset:792
	ds_read_b32 v50, v32 offset:924
	v_lshl_add_u64 v[20:21], v[40:41], 0, v[0:1]
	s_waitcnt lgkmcnt(6)
	v_cvt_pk_bf16_f32 v0, v2, v3
	s_waitcnt lgkmcnt(4)
	v_cvt_pk_bf16_f32 v1, v22, v23
	s_waitcnt lgkmcnt(2)
	v_cvt_pk_bf16_f32 v2, v39, v48
	s_waitcnt lgkmcnt(0)
	v_cvt_pk_bf16_f32 v3, v49, v50
	flat_store_dwordx4 v[20:21], v[0:3]
	ds_read_b32 v0, v32 offset:32
	ds_read_b32 v1, v32 offset:164
	ds_read_b32 v2, v32 offset:296
	ds_read_b32 v3, v32 offset:428
	ds_read_b32 v22, v32 offset:560
	ds_read_b32 v23, v32 offset:692
	ds_read_b32 v39, v32 offset:824
	ds_read_b32 v48, v32 offset:956
	v_lshl_add_u64 v[20:21], v[40:41], 0, v[42:43]
	s_waitcnt lgkmcnt(0)
	v_cvt_pk_bf16_f32 v0, v0, v1
	v_cvt_pk_bf16_f32 v1, v2, v3
	v_cvt_pk_bf16_f32 v2, v22, v23
	v_cvt_pk_bf16_f32 v3, v39, v48
	flat_store_dwordx4 v[20:21], v[0:3]
	ds_read_b32 v0, v32 offset:64
	ds_read_b32 v1, v32 offset:196
	ds_read_b32 v2, v32 offset:328
	ds_read_b32 v3, v32 offset:460
	ds_read_b32 v22, v32 offset:592
	ds_read_b32 v23, v32 offset:724
	ds_read_b32 v39, v32 offset:856
	ds_read_b32 v42, v32 offset:988
	v_lshl_add_u64 v[20:21], v[40:41], 0, v[44:45]
	s_waitcnt lgkmcnt(0)
	v_cvt_pk_bf16_f32 v0, v0, v1
	v_cvt_pk_bf16_f32 v1, v2, v3
	v_cvt_pk_bf16_f32 v2, v22, v23
	v_cvt_pk_bf16_f32 v3, v39, v42
	flat_store_dwordx4 v[20:21], v[0:3]
	ds_read_b32 v0, v32 offset:96
	ds_read_b32 v1, v32 offset:228
	ds_read_b32 v2, v32 offset:360
	ds_read_b32 v3, v32 offset:492
	ds_read_b32 v22, v32 offset:624
	ds_read_b32 v23, v32 offset:756
	ds_read_b32 v39, v32 offset:888
	ds_read_b32 v42, v32 offset:1020
	v_lshlrev_b64 v[20:21], 12, v[46:47]
	v_lshl_add_u64 v[20:21], v[40:41], 0, v[20:21]
	s_waitcnt lgkmcnt(0)
	v_cvt_pk_bf16_f32 v0, v0, v1
	v_cvt_pk_bf16_f32 v1, v2, v3
	v_cvt_pk_bf16_f32 v2, v22, v23
	v_cvt_pk_bf16_f32 v3, v39, v42
	flat_store_dwordx4 v[20:21], v[0:3]
	s_waitcnt lgkmcnt(0)
	s_branch .LBB0_320
